# DA unit prologue: per-tile class table (8 wave min/max reductions) batched: loads hoisted, butterfly rounds interleaved 4-wide
# baseline (speedup 1.0000x reference)
; #define lane mk_lane()
; __device__ __forceinline__ void attn_unit_da(const AttnUnit& U, char* lds) {
;     ...
;   for (int k = 0; k < 8; ++k) { const int t = wid * 8 + k; int v = U.posg[t * 64 + lane], mnv = v, mxv = v;
; #pragma unroll
;     for (int of = 1; of < 64; of <<= 1) { mnv = min(mnv, __shfl_xor(mnv, of)); mxv = max(mxv, __shfl_xor(mxv, of)); }
;     if (lane == 0) cls[t] = (mxv <= pmin && mxv < pmax) ? 0 : ((mnv >= pmax) ? 1 : 2); }
.LBB0_1918:
	s_or_b64 exec, exec, s[6:7]
	v_lshl_add_u32 v2, s69, 9, v243
	v_ashrrev_i32_e32 v3, 31, v2
	v_lshl_add_u64 v[2:3], v[2:3], 2, s[24:25]
	global_load_dword v20, v[2:3], off
	global_load_dword v21, v[2:3], off offset:256
	global_load_dword v22, v[2:3], off offset:512
	global_load_dword v23, v[2:3], off offset:768
	global_load_dword v24, v[2:3], off offset:1024
	global_load_dword v25, v[2:3], off offset:1280
	global_load_dword v26, v[2:3], off offset:1536
	global_load_dword v27, v[2:3], off offset:1792
	s_lshl_b32 s38, s69, 3
	s_waitcnt vmcnt(0)
	ds_bpermute_b32 v28, v6, v20
	ds_bpermute_b32 v29, v6, v21
	ds_bpermute_b32 v30, v6, v22
	ds_bpermute_b32 v31, v6, v23
	s_waitcnt lgkmcnt(0)
	v_min_i32_e32 v36, v20, v28
	v_max_i32_e32 v20, v20, v28
	v_min_i32_e32 v37, v21, v29
	v_max_i32_e32 v21, v21, v29
	v_min_i32_e32 v38, v22, v30
	v_max_i32_e32 v22, v22, v30
	v_min_i32_e32 v39, v23, v31
	v_max_i32_e32 v23, v23, v31
	ds_bpermute_b32 v28, v7, v36
	ds_bpermute_b32 v44, v7, v20
	ds_bpermute_b32 v29, v7, v37
	ds_bpermute_b32 v45, v7, v21
	ds_bpermute_b32 v30, v7, v38
	ds_bpermute_b32 v46, v7, v22
	ds_bpermute_b32 v31, v7, v39
	ds_bpermute_b32 v47, v7, v23
	s_waitcnt lgkmcnt(0)
	v_min_i32_e32 v36, v36, v28
	v_max_i32_e32 v20, v20, v44
	v_min_i32_e32 v37, v37, v29
	v_max_i32_e32 v21, v21, v45
	v_min_i32_e32 v38, v38, v30
	v_max_i32_e32 v22, v22, v46
	v_min_i32_e32 v39, v39, v31
	v_max_i32_e32 v23, v23, v47
	ds_bpermute_b32 v28, v8, v36
	ds_bpermute_b32 v44, v8, v20
	ds_bpermute_b32 v29, v8, v37
	ds_bpermute_b32 v45, v8, v21
	ds_bpermute_b32 v30, v8, v38
	ds_bpermute_b32 v46, v8, v22
	ds_bpermute_b32 v31, v8, v39
	ds_bpermute_b32 v47, v8, v23
	s_waitcnt lgkmcnt(0)
	v_min_i32_e32 v36, v36, v28
	v_max_i32_e32 v20, v20, v44
	v_min_i32_e32 v37, v37, v29
	v_max_i32_e32 v21, v21, v45
	v_min_i32_e32 v38, v38, v30
	v_max_i32_e32 v22, v22, v46
	v_min_i32_e32 v39, v39, v31
	v_max_i32_e32 v23, v23, v47
	ds_bpermute_b32 v28, v10, v36
	ds_bpermute_b32 v44, v10, v20
	ds_bpermute_b32 v29, v10, v37
	ds_bpermute_b32 v45, v10, v21
	ds_bpermute_b32 v30, v10, v38
	ds_bpermute_b32 v46, v10, v22
	ds_bpermute_b32 v31, v10, v39
	ds_bpermute_b32 v47, v10, v23
	s_waitcnt lgkmcnt(0)
	v_min_i32_e32 v36, v36, v28
	v_max_i32_e32 v20, v20, v44
	v_min_i32_e32 v37, v37, v29
	v_max_i32_e32 v21, v21, v45
	v_min_i32_e32 v38, v38, v30
	v_max_i32_e32 v22, v22, v46
	v_min_i32_e32 v39, v39, v31
	v_max_i32_e32 v23, v23, v47
	ds_bpermute_b32 v28, v11, v36
	ds_bpermute_b32 v44, v11, v20
	ds_bpermute_b32 v29, v11, v37
	ds_bpermute_b32 v45, v11, v21
	ds_bpermute_b32 v30, v11, v38
	ds_bpermute_b32 v46, v11, v22
	ds_bpermute_b32 v31, v11, v39
	ds_bpermute_b32 v47, v11, v23
	s_waitcnt lgkmcnt(0)
	v_min_i32_e32 v36, v36, v28
	v_max_i32_e32 v20, v20, v44
	v_min_i32_e32 v37, v37, v29
	v_max_i32_e32 v21, v21, v45
	v_min_i32_e32 v38, v38, v30
	v_max_i32_e32 v22, v22, v46
	v_min_i32_e32 v39, v39, v31
	v_max_i32_e32 v23, v23, v47
	ds_bpermute_b32 v28, v9, v36
	ds_bpermute_b32 v44, v9, v20
	ds_bpermute_b32 v29, v9, v37
	ds_bpermute_b32 v45, v9, v21
	ds_bpermute_b32 v30, v9, v38
	ds_bpermute_b32 v46, v9, v22
	ds_bpermute_b32 v31, v9, v39
	ds_bpermute_b32 v47, v9, v23
	s_waitcnt lgkmcnt(0)
	v_min_i32_e32 v36, v36, v28
	v_max_i32_e32 v20, v20, v44
	v_min_i32_e32 v37, v37, v29
	v_max_i32_e32 v21, v21, v45
	v_min_i32_e32 v38, v38, v30
	v_max_i32_e32 v22, v22, v46
	v_min_i32_e32 v39, v39, v31
	v_max_i32_e32 v23, v23, v47
	ds_bpermute_b32 v32, v6, v24
	ds_bpermute_b32 v33, v6, v25
	ds_bpermute_b32 v34, v6, v26
	ds_bpermute_b32 v35, v6, v27
	s_waitcnt lgkmcnt(0)
	v_min_i32_e32 v40, v24, v32
	v_max_i32_e32 v24, v24, v32
	v_min_i32_e32 v41, v25, v33
	v_max_i32_e32 v25, v25, v33
	v_min_i32_e32 v42, v26, v34
	v_max_i32_e32 v26, v26, v34
	v_min_i32_e32 v43, v27, v35
	v_max_i32_e32 v27, v27, v35
	ds_bpermute_b32 v32, v7, v40
	ds_bpermute_b32 v48, v7, v24
	ds_bpermute_b32 v33, v7, v41
	ds_bpermute_b32 v49, v7, v25
	ds_bpermute_b32 v34, v7, v42
	ds_bpermute_b32 v50, v7, v26
	ds_bpermute_b32 v35, v7, v43
	ds_bpermute_b32 v51, v7, v27
	s_waitcnt lgkmcnt(0)
	v_min_i32_e32 v40, v40, v32
	v_max_i32_e32 v24, v24, v48
	v_min_i32_e32 v41, v41, v33
	v_max_i32_e32 v25, v25, v49
	v_min_i32_e32 v42, v42, v34
	v_max_i32_e32 v26, v26, v50
	v_min_i32_e32 v43, v43, v35
	v_max_i32_e32 v27, v27, v51
	ds_bpermute_b32 v32, v8, v40
	ds_bpermute_b32 v48, v8, v24
	ds_bpermute_b32 v33, v8, v41
	ds_bpermute_b32 v49, v8, v25
	ds_bpermute_b32 v34, v8, v42
	ds_bpermute_b32 v50, v8, v26
	ds_bpermute_b32 v35, v8, v43
	ds_bpermute_b32 v51, v8, v27
	s_waitcnt lgkmcnt(0)
	v_min_i32_e32 v40, v40, v32
	v_max_i32_e32 v24, v24, v48
	v_min_i32_e32 v41, v41, v33
	v_max_i32_e32 v25, v25, v49
	v_min_i32_e32 v42, v42, v34
	v_max_i32_e32 v26, v26, v50
	v_min_i32_e32 v43, v43, v35
	v_max_i32_e32 v27, v27, v51
	ds_bpermute_b32 v32, v10, v40
	ds_bpermute_b32 v48, v10, v24
	ds_bpermute_b32 v33, v10, v41
	ds_bpermute_b32 v49, v10, v25
	ds_bpermute_b32 v34, v10, v42
	ds_bpermute_b32 v50, v10, v26
	ds_bpermute_b32 v35, v10, v43
	ds_bpermute_b32 v51, v10, v27
	s_waitcnt lgkmcnt(0)
	v_min_i32_e32 v40, v40, v32
	v_max_i32_e32 v24, v24, v48
	v_min_i32_e32 v41, v41, v33
	v_max_i32_e32 v25, v25, v49
	v_min_i32_e32 v42, v42, v34
	v_max_i32_e32 v26, v26, v50
	v_min_i32_e32 v43, v43, v35
	v_max_i32_e32 v27, v27, v51
	ds_bpermute_b32 v32, v11, v40
	ds_bpermute_b32 v48, v11, v24
	ds_bpermute_b32 v33, v11, v41
	ds_bpermute_b32 v49, v11, v25
	ds_bpermute_b32 v34, v11, v42
	ds_bpermute_b32 v50, v11, v26
	ds_bpermute_b32 v35, v11, v43
	ds_bpermute_b32 v51, v11, v27
	s_waitcnt lgkmcnt(0)
	v_min_i32_e32 v40, v40, v32
	v_max_i32_e32 v24, v24, v48
	v_min_i32_e32 v41, v41, v33
	v_max_i32_e32 v25, v25, v49
	v_min_i32_e32 v42, v42, v34
	v_max_i32_e32 v26, v26, v50
	v_min_i32_e32 v43, v43, v35
	v_max_i32_e32 v27, v27, v51
	ds_bpermute_b32 v32, v9, v40
	ds_bpermute_b32 v48, v9, v24
	ds_bpermute_b32 v33, v9, v41
	ds_bpermute_b32 v49, v9, v25
	ds_bpermute_b32 v34, v9, v42
	ds_bpermute_b32 v50, v9, v26
	ds_bpermute_b32 v35, v9, v43
	ds_bpermute_b32 v51, v9, v27
	s_waitcnt lgkmcnt(0)
	v_min_i32_e32 v40, v40, v32
	v_max_i32_e32 v24, v24, v48
	v_min_i32_e32 v41, v41, v33
	v_max_i32_e32 v25, v25, v49
	v_min_i32_e32 v42, v42, v34
	v_max_i32_e32 v26, v26, v50
	v_min_i32_e32 v43, v43, v35
	v_max_i32_e32 v27, v27, v51
	v_cmp_eq_u32_e32 vcc, 0, v243
	s_and_saveexec_b64 s[6:7], vcc
	s_cbranch_execz .LBB0_1934
; __device__ __forceinline__ int v_rd_base(int lane) { return ((lane & 3) << 3) | (((lane >> 2) & 3) << 6) | (((lane >> 4) & 1) << 5) | (((lane >> 5) & 1) << 8); }
; #define WAIT_BAR_0() asm volatile("s_waitcnt vmcnt(0) lgkmcnt(0)\n\ts_barrier" ::: "memory")
; #define WAIT_BAR_0() asm volatile("s_waitcnt vmcnt(0) lgkmcnt(0)\n\ts_barrier" ::: "memory")
; #define WAIT_BAR_0() asm volatile("s_waitcnt vmcnt(0) lgkmcnt(0)\n\ts_barrier" ::: "memory")
; #define lane mk_lane()
; __device__ __forceinline__ void attn_unit_da(const AttnUnit& U, char* lds) {
;     ...
;   for (int k = 0; k < 8; ++k) { const int t = wid * 8 + k; int v = U.posg[t * 64 + lane], mnv = v, mxv = v;
; #pragma unroll
;     for (int of = 1; of < 64; of <<= 1) { mnv = min(mnv, __shfl_xor(mnv, of)); mxv = max(mxv, __shfl_xor(mxv, of)); }
;     if (lane == 0) cls[t] = (mxv <= pmin && mxv < pmax) ? 0 : ((mnv >= pmax) ? 1 : 2); }
;   const unsigned kdst = lds0 + A_OFF_K + wid * 1024, vdst = lds0 + A_OFF_V + wid * 1024;
;   const int vb0 = (int)lds0 + A_OFF_V + v_rd_base(lane);
;   const long kstep = (long)KVBLK * U.ldk, vstep = (long)KVBLK * U.ldv;
;     ...
;   f32x16 p0, p1; float mn = 0.f, al = 1.f; bf16x8 pa0, pa1, pa2, pa3; const int NT = U.NT;
;   DMA_TILE(0, 0);
;   WAIT_BAR_0();
	v_cmp_ge_i32_e64 s[2:3], s72, v20
	v_cmp_gt_i32_e64 s[4:5], s71, v20
	v_cmp_gt_i32_e64 s[36:37], s71, v36
	s_and_b64 s[2:3], s[2:3], s[4:5]
	s_nop 0
	v_cndmask_b32_e64 v2, 1, 2, s[36:37]
	v_cndmask_b32_e64 v2, v2, 0, s[2:3]
	s_or_b32 s39, s38, 0
	s_lshl_b32 s39, s39, 2
	s_add_i32 s39, s39, 0x1c800
	v_mov_b32_e32 v3, s39
	ds_write_b32 v3, v2
	v_cmp_ge_i32_e64 s[2:3], s72, v21
	v_cmp_gt_i32_e64 s[4:5], s71, v21
	v_cmp_gt_i32_e64 s[36:37], s71, v37
	s_and_b64 s[2:3], s[2:3], s[4:5]
	s_nop 0
	v_cndmask_b32_e64 v2, 1, 2, s[36:37]
	v_cndmask_b32_e64 v2, v2, 0, s[2:3]
	s_or_b32 s39, s38, 1
	s_lshl_b32 s39, s39, 2
	s_add_i32 s39, s39, 0x1c800
	v_mov_b32_e32 v3, s39
	ds_write_b32 v3, v2
	v_cmp_ge_i32_e64 s[2:3], s72, v22
	v_cmp_gt_i32_e64 s[4:5], s71, v22
	v_cmp_gt_i32_e64 s[36:37], s71, v38
	s_and_b64 s[2:3], s[2:3], s[4:5]
	s_nop 0
	v_cndmask_b32_e64 v2, 1, 2, s[36:37]
	v_cndmask_b32_e64 v2, v2, 0, s[2:3]
	s_or_b32 s39, s38, 2
	s_lshl_b32 s39, s39, 2
	s_add_i32 s39, s39, 0x1c800
	v_mov_b32_e32 v3, s39
	ds_write_b32 v3, v2
	v_cmp_ge_i32_e64 s[2:3], s72, v23
	v_cmp_gt_i32_e64 s[4:5], s71, v23
	v_cmp_gt_i32_e64 s[36:37], s71, v39
	s_and_b64 s[2:3], s[2:3], s[4:5]
	s_nop 0
	v_cndmask_b32_e64 v2, 1, 2, s[36:37]
	v_cndmask_b32_e64 v2, v2, 0, s[2:3]
	s_or_b32 s39, s38, 3
	s_lshl_b32 s39, s39, 2
	s_add_i32 s39, s39, 0x1c800
	v_mov_b32_e32 v3, s39
	ds_write_b32 v3, v2
	v_cmp_ge_i32_e64 s[2:3], s72, v24
	v_cmp_gt_i32_e64 s[4:5], s71, v24
	v_cmp_gt_i32_e64 s[36:37], s71, v40
	s_and_b64 s[2:3], s[2:3], s[4:5]
	s_nop 0
	v_cndmask_b32_e64 v2, 1, 2, s[36:37]
	v_cndmask_b32_e64 v2, v2, 0, s[2:3]
	s_or_b32 s39, s38, 4
	s_lshl_b32 s39, s39, 2
	s_add_i32 s39, s39, 0x1c800
	v_mov_b32_e32 v3, s39
	ds_write_b32 v3, v2
	v_cmp_ge_i32_e64 s[2:3], s72, v25
	v_cmp_gt_i32_e64 s[4:5], s71, v25
	v_cmp_gt_i32_e64 s[36:37], s71, v41
	s_and_b64 s[2:3], s[2:3], s[4:5]
	s_nop 0
	v_cndmask_b32_e64 v2, 1, 2, s[36:37]
	v_cndmask_b32_e64 v2, v2, 0, s[2:3]
	s_or_b32 s39, s38, 5
	s_lshl_b32 s39, s39, 2
	s_add_i32 s39, s39, 0x1c800
	v_mov_b32_e32 v3, s39
	ds_write_b32 v3, v2
	v_cmp_ge_i32_e64 s[2:3], s72, v26
	v_cmp_gt_i32_e64 s[4:5], s71, v26
	v_cmp_gt_i32_e64 s[36:37], s71, v42
	s_and_b64 s[2:3], s[2:3], s[4:5]
	s_nop 0
	v_cndmask_b32_e64 v2, 1, 2, s[36:37]
	v_cndmask_b32_e64 v2, v2, 0, s[2:3]
	s_or_b32 s39, s38, 6
	s_lshl_b32 s39, s39, 2
	s_add_i32 s39, s39, 0x1c800
	v_mov_b32_e32 v3, s39
	ds_write_b32 v3, v2
	v_cmp_ge_i32_e64 s[2:3], s72, v27
	v_cmp_gt_i32_e64 s[4:5], s71, v27
	v_cmp_gt_i32_e64 s[36:37], s71, v43
	s_and_b64 s[2:3], s[2:3], s[4:5]
	s_nop 0
	v_cndmask_b32_e64 v2, 1, 2, s[36:37]
	v_cndmask_b32_e64 v2, v2, 0, s[2:3]
	s_or_b32 s39, s38, 7
	s_lshl_b32 s39, s39, 2
	s_add_i32 s39, s39, 0x1c800
	v_mov_b32_e32 v3, s39
	ds_write_b32 v3, v2
.LBB0_1934:
	s_or_b64 exec, exec, s[6:7]
	s_bfe_u32 s37, s11, 0x3000c
	s_lshl_b32 s24, s64, 7
	s_lshr_b32 s2, s8, 4
	s_and_b32 s2, s2, 1
	s_lshl_b32 s25, s2, 8
	s_mul_i32 s37, s37, 0x3000000
	s_lshl_b64 s[0:1], s[0:1], 1
	s_add_u32 s0, s37, s0
	s_addc_u32 s1, 0, s1
	s_add_u32 s0, s35, s0
	s_addc_u32 s1, s42, s1
	s_and_b32 s98, s66, 0xf00
	s_mul_i32 s98, s98, 0x3000
	s_add_u32 s0, s0, s98
	s_addc_u32 s1, s1, 0
	s_mulk_i32 s68, 0x3000
	s_add_u32 s2, s44, s68
	s_addc_u32 s3, s45, 0
	s_lshl_b32 s4, s24, 1
	s_add_u32 s5, s2, s18
	s_addc_u32 s6, s3, s19
	s_add_u32 s2, s5, s4
	s_addc_u32 s3, s6, 0
	s_add_u32 s2, s2, 0x1000
	s_addc_u32 s3, s3, 0
	s_add_u32 s4, s5, 0x2000
	s_addc_u32 s5, s6, 0
	s_add_u32 s2, s2, s98
	s_addc_u32 s3, s3, 0
	s_add_u32 s4, s4, s98
	s_addc_u32 s5, s5, 0
	s_lshl_b32 s6, s70, 2
	s_waitcnt lgkmcnt(1)
	v_mov_b32_e32 v6, v226
	s_add_i32 s24, s6, 0
	v_sub_u32_e32 v0, v0, v244
	s_add_i32 s24, s24, 0x18000
	v_bfe_u32 v8, v6, 4, 5
	v_cvt_f32_i32_e32 v130, v0
	s_lshl_b32 s37, s69, 10
	v_and_b32_e32 v0, 15, v6
	s_waitcnt lgkmcnt(0)
	v_lshrrev_b32_e32 v7, 4, v6
	v_lshlrev_b32_e32 v2, 2, v7
	v_bitop3_b32 v0, v2, v0, 12 bitop3:0x6c
	v_lshrrev_b32_e32 v2, 2, v7
	v_bitop3_b32 v0, v2, v0, 3 bitop3:0x6c
	v_mul_u32_u24_e32 v2, 0x1800, v8
	s_cmp_lg_u32 0, -1
	v_lshlrev_b32_e32 v2, 1, v2
	s_cselect_b32 s6, 0, 0
	v_lshl_or_b32 v0, v0, 4, v2
	s_add_i32 s37, s37, s6
	v_lshl_add_u64 v[2:3], s[2:3], 0, v[0:1]
	v_add_u32_e32 v0, 0x60000, v0
	s_add_i32 s38, s37, 0x10000
	s_mov_b32 s7, m0
	s_mov_b32 m0, s38
	s_nop 0
	global_load_lds_dwordx4 v[2:3], off
	s_mov_b32 m0, s7
	v_lshl_add_u64 v[2:3], s[2:3], 0, v[0:1]
	s_add_i32 s2, s37, 0x12000
	s_mov_b32 s3, m0
	s_mov_b32 m0, s2
	s_nop 0
	global_load_lds_dwordx4 v[2:3], off
	s_mov_b32 m0, s3
	v_and_b32_e32 v2, 0x60, v6
	v_lshlrev_b32_e32 v3, 3, v6
	v_and_or_b32 v9, v3, 24, v2
	v_lshrrev_b32_e32 v2, 1, v6
	v_lshrrev_b32_e32 v3, 5, v6
	v_bfe_u32 v0, v6, 2, 2
	v_and_b32_e32 v2, 8, v2
	v_and_b32_e32 v3, 4, v3
	v_or3_b32 v6, v3, v0, v2
	v_and_or_b32 v0, v7, 16, v6
	v_mul_u32_u24_e32 v0, 0x1800, v0
	v_or_b32_e32 v0, v0, v9
	v_or_b32_e32 v8, 32, v8
	v_lshlrev_b32_e32 v0, 1, v0
	v_lshl_add_u64 v[2:3], s[4:5], 0, v[0:1]
	v_and_or_b32 v0, v8, 48, v6
	v_mul_u32_u24_e32 v0, 0x1800, v0
	v_or_b32_e32 v0, v0, v9
	s_mov_b32 s2, m0
	s_mov_b32 m0, s37
	s_nop 0
	global_load_lds_dwordx4 v[2:3], off
	s_mov_b32 m0, s2
	v_lshl_add_u64 v[2:3], v[2:3], 0, s[22:23]
	v_lshlrev_b32_e32 v0, 1, v0
	s_add_i32 s2, s37, 0x4000
	s_mov_b32 s3, m0
	s_mov_b32 m0, s2
	s_nop 0
	global_load_lds_dwordx4 v[2:3], off
	s_mov_b32 m0, s3
	v_lshl_add_u64 v[2:3], s[4:5], 0, v[0:1]
	s_add_i32 s2, s37, 0x2000
	s_mov_b32 s3, m0
	s_mov_b32 m0, s2
	s_nop 0
	global_load_lds_dwordx4 v[2:3], off
	s_mov_b32 m0, s3
	v_lshl_add_u64 v[2:3], v[2:3], 0, s[22:23]
	s_add_i32 s2, s37, 0x6000
	s_mov_b32 s3, m0
	s_mov_b32 m0, s2
	s_nop 0
	global_load_lds_dwordx4 v[2:3], off
	s_mov_b32 m0, s3
	v_lshlrev_b32_e32 v2, 3, v243
	v_lshlrev_b32_e32 v3, 4, v243
	v_lshlrev_b32_e32 v239, 4, v5
	v_and_b32_e32 v6, 0xc0, v3
	v_and_b32_e32 v7, 0x118, v2
	v_lshlrev_b32_e32 v2, 2, v5
	v_lshlrev_b32_e32 v3, 6, v4
	v_and_b32_e32 v3, 0xc0, v3
	v_lshlrev_b32_e32 v14, 2, v4
	v_bitop3_b32 v3, v14, v3, 48 bitop3:0x6c
	v_add_u32_e32 v5, 32, v239
	v_bitop3_b32 v247, v5, v3, s60 bitop3:0x78
	v_add_u32_e32 v5, 64, v239
	v_bitop3_b32 v248, v5, v3, s60 bitop3:0x78
	v_add_u32_e32 v5, 0x60, v239
	v_bitop3_b32 v249, v5, v3, s60 bitop3:0x78
	v_add_u32_e32 v5, 0x80, v239
	v_bitop3_b32 v250, v5, v3, s60 bitop3:0x78
	v_add_u32_e32 v5, 0xa0, v239
	s_add_i32 s2, 0, 0x10000
	v_bitop3_b32 v252, v5, v3, s60 bitop3:0x78
	v_add_u32_e32 v5, 0xc0, v239
	v_lshlrev_b32_e32 v0, 1, v243
	v_bitop3_b32 v253, v5, v3, s60 bitop3:0x78
	v_add_u32_e32 v5, 0xe0, v239
	s_add_u32 s4, s54, s67
	v_bitop3_b32 v246, v3, v239, s60 bitop3:0x6c
	v_bitop3_b32 v254, v5, v3, s60 bitop3:0x78
	v_ashrrev_i32_e32 v3, 31, v2
	v_and_or_b32 v0, v0, 32, v7
	s_addc_u32 s5, s55, 0
	v_mov_b32_e32 v14, v1
	v_mov_b32_e32 v15, v1
	s_waitcnt vmcnt(0) lgkmcnt(0)
	s_barrier
; #define WAIT_BAR_0() asm volatile("s_waitcnt vmcnt(0) lgkmcnt(0)\n\ts_barrier" ::: "memory")
; #define WAIT_BAR_0() asm volatile("s_waitcnt vmcnt(0) lgkmcnt(0)\n\ts_barrier" ::: "memory")
; #define WAIT_BAR_0() asm volatile("s_waitcnt vmcnt(0) lgkmcnt(0)\n\ts_barrier" ::: "memory")
; __device__ __forceinline__ void attn_unit_da(const AttnUnit& U, char* lds) {
;     ...
;   float m_reg = -1e30f, l_reg = 0; f32x16 o[8] = {}; bf16x8 qr[ND0];
;     ...
;   f32x16 p0, p1; float mn = 0.f, al = 1.f; bf16x8 pa0, pa1, pa2, pa3; const int NT = U.NT;
;   DMA_TILE(0, 0);
;   WAIT_BAR_0();
;   for (int j = 0; j < NT; ++j) {
;     const int st = j & 1;
;     if (j + 1 < NT) DMA_TILE(j + 1, st ^ 1);
;     float rc;
;     { const int c_ = __builtin_amdgcn_readfirstlane(cls[j]); const float* ak_ = aux + j * KVBLK;
;       if (c_ < 2) { rc = (c_ == 0) ? pq * U.nsl : -pq * U.nsl;
	v_lshl_add_u32 v245, v4, 8, s2
	v_lshl_add_u32 v251, v4, 2, s24
	v_add3_u32 v237, v6, s6, v0
	v_lshl_add_u64 v[232:233], v[2:3], 2, s[4:5]
	v_mov_b32_e32 v0, v1
	v_mov_b32_e32 v2, v1
	v_mov_b32_e32 v3, v1
	v_mov_b32_e32 v4, v1
	v_mov_b32_e32 v5, v1
	v_mov_b32_e32 v6, v1
	v_mov_b32_e32 v7, v1
	v_mov_b32_e32 v8, v1
	v_mov_b32_e32 v9, v1
	v_mov_b32_e32 v10, v1
	v_mov_b32_e32 v11, v1
	v_mov_b32_e32 v12, v1
	v_mov_b32_e32 v13, v1
	v_mov_b64_e32 v[128:129], v[14:15]
	v_mov_b64_e32 v[112:113], v[14:15]
	v_mov_b64_e32 v[96:97], v[14:15]
	v_mov_b64_e32 v[80:81], v[14:15]
	v_mov_b64_e32 v[64:65], v[14:15]
	v_mov_b64_e32 v[48:49], v[14:15]
	v_mov_b64_e32 v[32:33], v[14:15]
	v_mov_b64_e32 v[126:127], v[12:13]
	v_mov_b64_e32 v[124:125], v[10:11]
	v_mov_b64_e32 v[122:123], v[8:9]
	v_mov_b64_e32 v[120:121], v[6:7]
	v_mov_b64_e32 v[118:119], v[4:5]
	v_mov_b64_e32 v[116:117], v[2:3]
	v_mov_b64_e32 v[114:115], v[0:1]
	v_mov_b64_e32 v[110:111], v[12:13]
	v_mov_b64_e32 v[108:109], v[10:11]
	v_mov_b64_e32 v[106:107], v[8:9]
	v_mov_b64_e32 v[104:105], v[6:7]
	v_mov_b64_e32 v[102:103], v[4:5]
	v_mov_b64_e32 v[100:101], v[2:3]
	v_mov_b64_e32 v[98:99], v[0:1]
	v_mov_b64_e32 v[94:95], v[12:13]
	v_mov_b64_e32 v[92:93], v[10:11]
	v_mov_b64_e32 v[90:91], v[8:9]
	v_mov_b64_e32 v[88:89], v[6:7]
	v_mov_b64_e32 v[86:87], v[4:5]
	v_mov_b64_e32 v[84:85], v[2:3]
	v_mov_b64_e32 v[82:83], v[0:1]
	v_mov_b64_e32 v[78:79], v[12:13]
	v_mov_b64_e32 v[76:77], v[10:11]
	v_mov_b64_e32 v[74:75], v[8:9]
	v_mov_b64_e32 v[72:73], v[6:7]
	v_mov_b64_e32 v[70:71], v[4:5]
	v_mov_b64_e32 v[68:69], v[2:3]
	v_mov_b64_e32 v[66:67], v[0:1]
	v_mov_b64_e32 v[62:63], v[12:13]
	v_mov_b64_e32 v[60:61], v[10:11]
	v_mov_b64_e32 v[58:59], v[8:9]
	v_mov_b64_e32 v[56:57], v[6:7]
	v_mov_b64_e32 v[54:55], v[4:5]
	v_mov_b64_e32 v[52:53], v[2:3]
	v_mov_b64_e32 v[50:51], v[0:1]
	v_mov_b64_e32 v[46:47], v[12:13]
	v_mov_b64_e32 v[44:45], v[10:11]
	v_mov_b64_e32 v[42:43], v[8:9]
	v_mov_b64_e32 v[40:41], v[6:7]
	v_mov_b64_e32 v[38:39], v[4:5]
	v_mov_b64_e32 v[36:37], v[2:3]
	v_mov_b64_e32 v[34:35], v[0:1]
	v_mov_b64_e32 v[30:31], v[12:13]
	v_mov_b64_e32 v[28:29], v[10:11]
	v_mov_b64_e32 v[26:27], v[8:9]
	v_mov_b64_e32 v[24:25], v[6:7]
	v_mov_b64_e32 v[22:23], v[4:5]
	v_mov_b64_e32 v[20:21], v[2:3]
	v_mov_b64_e32 v[18:19], v[0:1]
	v_mov_b64_e32 v[16:17], v[14:15]
	s_mov_b32 s36, 0
	v_cmp_gt_u32_e64 s[2:3], 32, v243
	v_mov_b32_e32 v230, v228
	v_mov_b32_e32 v231, v228
	v_mov_b32_e32 v131, v130
	v_mov_b32_e32 v132, v130
	v_mov_b32_e32 v133, v130
	v_mov_b32_e32 v134, v130
	v_mov_b32_e32 v135, v130
	v_mov_b32_e32 v136, v130
	v_mov_b32_e32 v137, v130
	v_mov_b32_e32 v138, v130
	v_mov_b32_e32 v139, v130
	v_mov_b32_e32 v140, v130
	v_mov_b32_e32 v141, v130
	v_mov_b32_e32 v142, v130
	v_mov_b32_e32 v240, 0
	v_mov_b32_e32 v238, 0xf149f2ca
	s_and_b32 s98, s66, 0xf00
	s_lshl_b32 s6, s98, 2
	s_mov_b32 s7, 0
	s_and_b32 s99, s66, 0xf00
	s_lshr_b32 s99, s99, 4
	s_add_i32 s39, s99, 0x1c800
	s_and_b32 s99, s66, 0xf00
	s_lshl_b32 s99, s99, 2
	v_add_u32_e32 v227, s99, v239
	v_mov_b32_e32 v143, v130
	v_mov_b32_e32 v144, v130
	v_mov_b32_e32 v145, v130
	v_mov_b64_e32 v[14:15], v[12:13]
	v_mov_b64_e32 v[12:13], v[10:11]
	v_mov_b64_e32 v[10:11], v[8:9]
	v_mov_b64_e32 v[8:9], v[6:7]
	v_mov_b64_e32 v[6:7], v[4:5]
	v_mov_b64_e32 v[4:5], v[2:3]
	v_mov_b64_e32 v[2:3], v[0:1]
	s_branch .LBB0_1938
